# FF1 tile epilogue rewritten: relu^2->bf16 row segments paired with v_permlane16_swap into 16-byte stores (16 instead of 32 stores per wave-tile), on top of unrolled K-loops
# speedup vs baseline: 1.0172x; 1.0172x over previous
;     __device__ __forceinline__ void fin(int m, int n, f32x4 v, f32x4, f32x4) const { horiz(m, n, v); }
;     __device__ __forceinline__ void fin(int m, int n, f32x4 v, f32x4, f32x4) const { horiz(m, n, v); }
; template <int MI, bool SWAP, class Epi> ...
;     ...
;     if (SWAP) {
; #pragma unroll
;         for (int i2 = 0; i2 < MI / 2; ++i2) {
;             f32x4 pa[2][4], pg[2][4];
; #pragma unroll
;             for (int ii = 0; ii < 2; ++ii)
; #pragma unroll
;                 for (int j = 0; j < 4; ++j) epi.pre(m0 + wr * (MI * 16) + (i2 * 2 + ii) * 16 + fr, n0 + wc * 64 + j * 16 + fq * 4, pa[ii][j], pg[ii][j]);
;             __builtin_amdgcn_sched_barrier(0);
; #pragma unroll
;             for (int ii = 0; ii < 2; ++ii)
; #pragma unroll
;                 for (int j = 0; j < 4; ++j) epi.fin(m0 + wr * (MI * 16) + (i2 * 2 + ii) * 16 + fr, n0 + wc * 64 + j * 16 + fq * 4, acc[i2 * 2 + ii][j], pa[ii][j], pg[ii][j]);
;         }
;     __device__ __forceinline__ void horiz(int m, int n, f32x4 v) const {
;         float a = fmaxf(v[0], 0.f), b = fmaxf(v[1], 0.f), c = fmaxf(v[2], 0.f), d = fmaxf(v[3], 0.f);
;         u32x2 w; w.x = pack2(a * a, b * b); w.y = pack2(c * c, d * d);
;         *(u32x2*)(HID + (size_t)m * DFF + n) = w;
;     }
.LBB0_2163:
	v_or_b32_e32 v128, s11, v221
	v_lshl_or_b32 v129, v218, 2, s10
	v_add_u32_e32 v128, s25, v128
	v_or_b32_e32 v130, s26, v129
	v_ashrrev_i32_e32 v129, 31, v128
	v_lshlrev_b64 v[132:133], 13, v[128:129]
	v_ashrrev_i32_e32 v131, 31, v130
	v_lshl_add_u64 v[132:133], s[68:69], 0, v[132:133]
	v_lshlrev_b64 v[128:129], 1, v[130:131]
	v_lshl_add_u64 v[130:131], v[132:133], 0, v[128:129]
	v_and_b32_e32 v128, 1, v218
	v_mul_u32_u24_e32 v128, 24, v128
	v_mov_b32_e32 v129, 0
	v_lshl_add_u64 v[130:131], v[130:131], 0, v[128:129]
	s_mov_b64 vcc, 0x20000
	v_writelane_b32 v253, s56, 47
	v_writelane_b32 v253, s55, 48
	v_max_f32_e32 v112, v112, v112
	v_max_f32_e32 v113, v113, v113
	v_max_f32_e32 v114, v114, v114
	v_max_f32_e32 v115, v115, v115
	v_max_f32_e32 v116, v116, v116
	v_max_f32_e32 v117, v117, v117
	v_max_f32_e32 v118, v118, v118
	v_max_f32_e32 v119, v119, v119
	v_max_f32_e32 v120, v120, v120
	v_max_f32_e32 v121, v121, v121
	v_max_f32_e32 v122, v122, v122
	v_max_f32_e32 v123, v123, v123
	v_max_f32_e32 v124, v124, v124
	v_max_f32_e32 v125, v125, v125
	v_max_f32_e32 v126, v126, v126
	v_max_f32_e32 v127, v127, v127
	v_max_f32_e32 v112, 0, v112
	v_max_f32_e32 v113, 0, v113
	v_max_f32_e32 v114, 0, v114
	v_max_f32_e32 v115, 0, v115
	v_max_f32_e32 v116, 0, v116
	v_max_f32_e32 v117, 0, v117
	v_max_f32_e32 v118, 0, v118
	v_max_f32_e32 v119, 0, v119
	v_max_f32_e32 v120, 0, v120
	v_max_f32_e32 v121, 0, v121
	v_max_f32_e32 v122, 0, v122
	v_max_f32_e32 v123, 0, v123
	v_max_f32_e32 v124, 0, v124
	v_max_f32_e32 v125, 0, v125
	v_max_f32_e32 v126, 0, v126
	v_max_f32_e32 v127, 0, v127
	v_mul_f32_e32 v112, v112, v112
	v_mul_f32_e32 v113, v113, v113
	v_mul_f32_e32 v114, v114, v114
	v_mul_f32_e32 v115, v115, v115
	v_mul_f32_e32 v116, v116, v116
	v_mul_f32_e32 v117, v117, v117
	v_mul_f32_e32 v118, v118, v118
	v_mul_f32_e32 v119, v119, v119
	v_mul_f32_e32 v120, v120, v120
	v_mul_f32_e32 v121, v121, v121
	v_mul_f32_e32 v122, v122, v122
	v_mul_f32_e32 v123, v123, v123
	v_mul_f32_e32 v124, v124, v124
	v_mul_f32_e32 v125, v125, v125
	v_mul_f32_e32 v126, v126, v126
	v_mul_f32_e32 v127, v127, v127
	v_cvt_pk_bf16_f32 v124, v124, v125
	v_cvt_pk_bf16_f32 v125, v126, v127
	v_cvt_pk_bf16_f32 v126, v120, v121
	v_cvt_pk_bf16_f32 v127, v122, v123
	v_cvt_pk_bf16_f32 v116, v116, v117
	v_cvt_pk_bf16_f32 v117, v118, v119
	v_cvt_pk_bf16_f32 v118, v112, v113
	v_cvt_pk_bf16_f32 v119, v114, v115
	s_nop 1
	v_permlane16_swap_b32_e32 v124, v126
	v_permlane16_swap_b32_e32 v125, v127
	v_permlane16_swap_b32_e32 v116, v118
	v_permlane16_swap_b32_e32 v117, v119
	v_lshl_add_u64 v[132:133], v[130:131], 0, vcc
	s_nop 0
	global_store_dwordx4 v[130:131], v[124:127], off
	global_store_dwordx4 v[130:131], v[116:119], off offset:64
	v_max_f32_e32 v96, v96, v96
	v_max_f32_e32 v97, v97, v97
	v_max_f32_e32 v98, v98, v98
	v_max_f32_e32 v99, v99, v99
	v_max_f32_e32 v100, v100, v100
	v_max_f32_e32 v101, v101, v101
	v_max_f32_e32 v102, v102, v102
	v_max_f32_e32 v103, v103, v103
	v_max_f32_e32 v104, v104, v104
	v_max_f32_e32 v105, v105, v105
	v_max_f32_e32 v106, v106, v106
	v_max_f32_e32 v107, v107, v107
	v_max_f32_e32 v108, v108, v108
	v_max_f32_e32 v109, v109, v109
	v_max_f32_e32 v110, v110, v110
	v_max_f32_e32 v111, v111, v111
	v_max_f32_e32 v96, 0, v96
	v_max_f32_e32 v97, 0, v97
	v_max_f32_e32 v98, 0, v98
	v_max_f32_e32 v99, 0, v99
	v_max_f32_e32 v100, 0, v100
	v_max_f32_e32 v101, 0, v101
	v_max_f32_e32 v102, 0, v102
	v_max_f32_e32 v103, 0, v103
	v_max_f32_e32 v104, 0, v104
	v_max_f32_e32 v105, 0, v105
	v_max_f32_e32 v106, 0, v106
	v_max_f32_e32 v107, 0, v107
	v_max_f32_e32 v108, 0, v108
	v_max_f32_e32 v109, 0, v109
	v_max_f32_e32 v110, 0, v110
	v_max_f32_e32 v111, 0, v111
	v_mul_f32_e32 v96, v96, v96
	v_mul_f32_e32 v97, v97, v97
	v_mul_f32_e32 v98, v98, v98
	v_mul_f32_e32 v99, v99, v99
	v_mul_f32_e32 v100, v100, v100
	v_mul_f32_e32 v101, v101, v101
	v_mul_f32_e32 v102, v102, v102
	v_mul_f32_e32 v103, v103, v103
	v_mul_f32_e32 v104, v104, v104
	v_mul_f32_e32 v105, v105, v105
	v_mul_f32_e32 v106, v106, v106
	v_mul_f32_e32 v107, v107, v107
	v_mul_f32_e32 v108, v108, v108
	v_mul_f32_e32 v109, v109, v109
	v_mul_f32_e32 v110, v110, v110
	v_mul_f32_e32 v111, v111, v111
	v_cvt_pk_bf16_f32 v108, v108, v109
	v_cvt_pk_bf16_f32 v109, v110, v111
	v_cvt_pk_bf16_f32 v110, v104, v105
	v_cvt_pk_bf16_f32 v111, v106, v107
	v_cvt_pk_bf16_f32 v100, v100, v101
	v_cvt_pk_bf16_f32 v101, v102, v103
	v_cvt_pk_bf16_f32 v102, v96, v97
	v_cvt_pk_bf16_f32 v103, v98, v99
	s_nop 1
	v_permlane16_swap_b32_e32 v108, v110
	v_permlane16_swap_b32_e32 v109, v111
	v_permlane16_swap_b32_e32 v100, v102
	v_permlane16_swap_b32_e32 v101, v103
	v_lshl_add_u64 v[130:131], v[132:133], 0, vcc
	s_nop 0
	global_store_dwordx4 v[132:133], v[108:111], off
	global_store_dwordx4 v[132:133], v[100:103], off offset:64
	v_max_f32_e32 v80, v80, v80
	v_max_f32_e32 v81, v81, v81
	v_max_f32_e32 v82, v82, v82
	v_max_f32_e32 v83, v83, v83
	v_max_f32_e32 v84, v84, v84
	v_max_f32_e32 v85, v85, v85
	v_max_f32_e32 v86, v86, v86
	v_max_f32_e32 v87, v87, v87
	v_max_f32_e32 v88, v88, v88
	v_max_f32_e32 v89, v89, v89
	v_max_f32_e32 v90, v90, v90
	v_max_f32_e32 v91, v91, v91
	v_max_f32_e32 v92, v92, v92
	v_max_f32_e32 v93, v93, v93
	v_max_f32_e32 v94, v94, v94
	v_max_f32_e32 v95, v95, v95
	v_max_f32_e32 v80, 0, v80
	v_max_f32_e32 v81, 0, v81
	v_max_f32_e32 v82, 0, v82
	v_max_f32_e32 v83, 0, v83
	v_max_f32_e32 v84, 0, v84
	v_max_f32_e32 v85, 0, v85
	v_max_f32_e32 v86, 0, v86
	v_max_f32_e32 v87, 0, v87
	v_max_f32_e32 v88, 0, v88
	v_max_f32_e32 v89, 0, v89
	v_max_f32_e32 v90, 0, v90
	v_max_f32_e32 v91, 0, v91
	v_max_f32_e32 v92, 0, v92
	v_max_f32_e32 v93, 0, v93
;     __device__ __forceinline__ void fin(int m, int n, f32x4 v, f32x4, f32x4) const { horiz(m, n, v); }
;     __device__ __forceinline__ void fin(int m, int n, f32x4 v, f32x4, f32x4) const { horiz(m, n, v); }
; template <int MI, bool SWAP, class Epi> ...
;     ...
;     if (SWAP) {
; #pragma unroll
;         for (int i2 = 0; i2 < MI / 2; ++i2) {
;             f32x4 pa[2][4], pg[2][4];
; #pragma unroll
;             for (int ii = 0; ii < 2; ++ii)
; #pragma unroll
;                 for (int j = 0; j < 4; ++j) epi.pre(m0 + wr * (MI * 16) + (i2 * 2 + ii) * 16 + fr, n0 + wc * 64 + j * 16 + fq * 4, pa[ii][j], pg[ii][j]);
;             __builtin_amdgcn_sched_barrier(0);
; #pragma unroll
;             for (int ii = 0; ii < 2; ++ii)
; #pragma unroll
;                 for (int j = 0; j < 4; ++j) epi.fin(m0 + wr * (MI * 16) + (i2 * 2 + ii) * 16 + fr, n0 + wc * 64 + j * 16 + fq * 4, acc[i2 * 2 + ii][j], pa[ii][j], pg[ii][j]);
;         }
;     __device__ __forceinline__ void horiz(int m, int n, f32x4 v) const {
;         float a = fmaxf(v[0], 0.f), b = fmaxf(v[1], 0.f), c = fmaxf(v[2], 0.f), d = fmaxf(v[3], 0.f);
;         u32x2 w; w.x = pack2(a * a, b * b); w.y = pack2(c * c, d * d);
;         *(u32x2*)(HID + (size_t)m * DFF + n) = w;
;     }
	v_max_f32_e32 v94, 0, v94
	v_max_f32_e32 v95, 0, v95
	v_mul_f32_e32 v80, v80, v80
	v_mul_f32_e32 v81, v81, v81
	v_mul_f32_e32 v82, v82, v82
	v_mul_f32_e32 v83, v83, v83
	v_mul_f32_e32 v84, v84, v84
	v_mul_f32_e32 v85, v85, v85
	v_mul_f32_e32 v86, v86, v86
	v_mul_f32_e32 v87, v87, v87
	v_mul_f32_e32 v88, v88, v88
	v_mul_f32_e32 v89, v89, v89
	v_mul_f32_e32 v90, v90, v90
	v_mul_f32_e32 v91, v91, v91
	v_mul_f32_e32 v92, v92, v92
	v_mul_f32_e32 v93, v93, v93
	v_mul_f32_e32 v94, v94, v94
	v_mul_f32_e32 v95, v95, v95
	v_cvt_pk_bf16_f32 v92, v92, v93
	v_cvt_pk_bf16_f32 v93, v94, v95
	v_cvt_pk_bf16_f32 v94, v88, v89
	v_cvt_pk_bf16_f32 v95, v90, v91
	v_cvt_pk_bf16_f32 v84, v84, v85
	v_cvt_pk_bf16_f32 v85, v86, v87
	v_cvt_pk_bf16_f32 v86, v80, v81
	v_cvt_pk_bf16_f32 v87, v82, v83
	s_nop 1
	v_permlane16_swap_b32_e32 v92, v94
	v_permlane16_swap_b32_e32 v93, v95
	v_permlane16_swap_b32_e32 v84, v86
	v_permlane16_swap_b32_e32 v85, v87
	v_lshl_add_u64 v[132:133], v[130:131], 0, vcc
	s_nop 0
	global_store_dwordx4 v[130:131], v[92:95], off
	global_store_dwordx4 v[130:131], v[84:87], off offset:64
	v_max_f32_e32 v64, v64, v64
	v_max_f32_e32 v65, v65, v65
	v_max_f32_e32 v66, v66, v66
	v_max_f32_e32 v67, v67, v67
	v_max_f32_e32 v68, v68, v68
	v_max_f32_e32 v69, v69, v69
	v_max_f32_e32 v70, v70, v70
	v_max_f32_e32 v71, v71, v71
	v_max_f32_e32 v72, v72, v72
	v_max_f32_e32 v73, v73, v73
	v_max_f32_e32 v74, v74, v74
	v_max_f32_e32 v75, v75, v75
	v_max_f32_e32 v76, v76, v76
	v_max_f32_e32 v77, v77, v77
	v_max_f32_e32 v78, v78, v78
	v_max_f32_e32 v79, v79, v79
	v_max_f32_e32 v64, 0, v64
	v_max_f32_e32 v65, 0, v65
	v_max_f32_e32 v66, 0, v66
	v_max_f32_e32 v67, 0, v67
	v_max_f32_e32 v68, 0, v68
	v_max_f32_e32 v69, 0, v69
	v_max_f32_e32 v70, 0, v70
	v_max_f32_e32 v71, 0, v71
	v_max_f32_e32 v72, 0, v72
	v_max_f32_e32 v73, 0, v73
	v_max_f32_e32 v74, 0, v74
	v_max_f32_e32 v75, 0, v75
	v_max_f32_e32 v76, 0, v76
	v_max_f32_e32 v77, 0, v77
	v_max_f32_e32 v78, 0, v78
	v_max_f32_e32 v79, 0, v79
	v_mul_f32_e32 v64, v64, v64
	v_mul_f32_e32 v65, v65, v65
	v_mul_f32_e32 v66, v66, v66
	v_mul_f32_e32 v67, v67, v67
	v_mul_f32_e32 v68, v68, v68
	v_mul_f32_e32 v69, v69, v69
	v_mul_f32_e32 v70, v70, v70
	v_mul_f32_e32 v71, v71, v71
	v_mul_f32_e32 v72, v72, v72
	v_mul_f32_e32 v73, v73, v73
	v_mul_f32_e32 v74, v74, v74
	v_mul_f32_e32 v75, v75, v75
	v_mul_f32_e32 v76, v76, v76
	v_mul_f32_e32 v77, v77, v77
	v_mul_f32_e32 v78, v78, v78
	v_mul_f32_e32 v79, v79, v79
	v_cvt_pk_bf16_f32 v76, v76, v77
	v_cvt_pk_bf16_f32 v77, v78, v79
	v_cvt_pk_bf16_f32 v78, v72, v73
	v_cvt_pk_bf16_f32 v79, v74, v75
	v_cvt_pk_bf16_f32 v68, v68, v69
	v_cvt_pk_bf16_f32 v69, v70, v71
	v_cvt_pk_bf16_f32 v70, v64, v65
	v_cvt_pk_bf16_f32 v71, v66, v67
	s_nop 1
	v_permlane16_swap_b32_e32 v76, v78
	v_permlane16_swap_b32_e32 v77, v79
	v_permlane16_swap_b32_e32 v68, v70
	v_permlane16_swap_b32_e32 v69, v71
	v_lshl_add_u64 v[130:131], v[132:133], 0, vcc
	s_nop 0
	global_store_dwordx4 v[132:133], v[76:79], off
	global_store_dwordx4 v[132:133], v[68:71], off offset:64
	v_max_f32_e32 v48, v48, v48
	v_max_f32_e32 v49, v49, v49
	v_max_f32_e32 v50, v50, v50
	v_max_f32_e32 v51, v51, v51
	v_max_f32_e32 v52, v52, v52
	v_max_f32_e32 v53, v53, v53
	v_max_f32_e32 v54, v54, v54
	v_max_f32_e32 v55, v55, v55
	v_max_f32_e32 v56, v56, v56
	v_max_f32_e32 v57, v57, v57
	v_max_f32_e32 v58, v58, v58
	v_max_f32_e32 v59, v59, v59
	v_max_f32_e32 v60, v60, v60
	v_max_f32_e32 v61, v61, v61
	v_max_f32_e32 v62, v62, v62
	v_max_f32_e32 v63, v63, v63
	v_max_f32_e32 v48, 0, v48
	v_max_f32_e32 v49, 0, v49
	v_max_f32_e32 v50, 0, v50
	v_max_f32_e32 v51, 0, v51
	v_max_f32_e32 v52, 0, v52
	v_max_f32_e32 v53, 0, v53
	v_max_f32_e32 v54, 0, v54
	v_max_f32_e32 v55, 0, v55
	v_max_f32_e32 v56, 0, v56
	v_max_f32_e32 v57, 0, v57
	v_max_f32_e32 v58, 0, v58
	v_max_f32_e32 v59, 0, v59
	v_max_f32_e32 v60, 0, v60
	v_max_f32_e32 v61, 0, v61
	v_max_f32_e32 v62, 0, v62
	v_max_f32_e32 v63, 0, v63
	v_mul_f32_e32 v48, v48, v48
	v_mul_f32_e32 v49, v49, v49
	v_mul_f32_e32 v50, v50, v50
	v_mul_f32_e32 v51, v51, v51
	v_mul_f32_e32 v52, v52, v52
	v_mul_f32_e32 v53, v53, v53
	v_mul_f32_e32 v54, v54, v54
	v_mul_f32_e32 v55, v55, v55
	v_mul_f32_e32 v56, v56, v56
	v_mul_f32_e32 v57, v57, v57
	v_mul_f32_e32 v58, v58, v58
	v_mul_f32_e32 v59, v59, v59
	v_mul_f32_e32 v60, v60, v60
	v_mul_f32_e32 v61, v61, v61
	v_mul_f32_e32 v62, v62, v62
	v_mul_f32_e32 v63, v63, v63
	v_cvt_pk_bf16_f32 v60, v60, v61
	v_cvt_pk_bf16_f32 v61, v62, v63
	v_cvt_pk_bf16_f32 v62, v56, v57
	v_cvt_pk_bf16_f32 v63, v58, v59
	v_cvt_pk_bf16_f32 v52, v52, v53
	v_cvt_pk_bf16_f32 v53, v54, v55
	v_cvt_pk_bf16_f32 v54, v48, v49
	v_cvt_pk_bf16_f32 v55, v50, v51
	s_nop 1
	v_permlane16_swap_b32_e32 v60, v62
	v_permlane16_swap_b32_e32 v61, v63
	v_permlane16_swap_b32_e32 v52, v54
	v_permlane16_swap_b32_e32 v53, v55
	v_lshl_add_u64 v[132:133], v[130:131], 0, vcc
	s_nop 0
	global_store_dwordx4 v[130:131], v[60:63], off
	global_store_dwordx4 v[130:131], v[52:55], off offset:64
	v_max_f32_e32 v32, v32, v32
	v_max_f32_e32 v33, v33, v33
	v_max_f32_e32 v34, v34, v34
	v_max_f32_e32 v35, v35, v35
	v_max_f32_e32 v36, v36, v36
	v_max_f32_e32 v37, v37, v37
	v_max_f32_e32 v38, v38, v38
	v_max_f32_e32 v39, v39, v39
	v_max_f32_e32 v40, v40, v40
	v_max_f32_e32 v41, v41, v41
	v_max_f32_e32 v42, v42, v42
	v_max_f32_e32 v43, v43, v43
	v_max_f32_e32 v44, v44, v44
;     __device__ __forceinline__ void fin(int m, int n, f32x4 v, f32x4, f32x4) const { horiz(m, n, v); }
;     __device__ __forceinline__ void fin(int m, int n, f32x4 v, f32x4, f32x4) const { horiz(m, n, v); }
; template <int MI, bool SWAP, class Epi> ...
;     ...
;     if (SWAP) {
; #pragma unroll
;         for (int i2 = 0; i2 < MI / 2; ++i2) {
;             f32x4 pa[2][4], pg[2][4];
; #pragma unroll
;             for (int ii = 0; ii < 2; ++ii)
; #pragma unroll
;                 for (int j = 0; j < 4; ++j) epi.pre(m0 + wr * (MI * 16) + (i2 * 2 + ii) * 16 + fr, n0 + wc * 64 + j * 16 + fq * 4, pa[ii][j], pg[ii][j]);
;             __builtin_amdgcn_sched_barrier(0);
; #pragma unroll
;             for (int ii = 0; ii < 2; ++ii)
; #pragma unroll
;                 for (int j = 0; j < 4; ++j) epi.fin(m0 + wr * (MI * 16) + (i2 * 2 + ii) * 16 + fr, n0 + wc * 64 + j * 16 + fq * 4, acc[i2 * 2 + ii][j], pa[ii][j], pg[ii][j]);
;         }
;     __device__ __forceinline__ void horiz(int m, int n, f32x4 v) const {
;         float a = fmaxf(v[0], 0.f), b = fmaxf(v[1], 0.f), c = fmaxf(v[2], 0.f), d = fmaxf(v[3], 0.f);
;         u32x2 w; w.x = pack2(a * a, b * b); w.y = pack2(c * c, d * d);
;         *(u32x2*)(HID + (size_t)m * DFF + n) = w;
;     }
	v_max_f32_e32 v45, v45, v45
	v_max_f32_e32 v46, v46, v46
	v_max_f32_e32 v47, v47, v47
	v_max_f32_e32 v32, 0, v32
	v_max_f32_e32 v33, 0, v33
	v_max_f32_e32 v34, 0, v34
	v_max_f32_e32 v35, 0, v35
	v_max_f32_e32 v36, 0, v36
	v_max_f32_e32 v37, 0, v37
	v_max_f32_e32 v38, 0, v38
	v_max_f32_e32 v39, 0, v39
	v_max_f32_e32 v40, 0, v40
	v_max_f32_e32 v41, 0, v41
	v_max_f32_e32 v42, 0, v42
	v_max_f32_e32 v43, 0, v43
	v_max_f32_e32 v44, 0, v44
	v_max_f32_e32 v45, 0, v45
	v_max_f32_e32 v46, 0, v46
	v_max_f32_e32 v47, 0, v47
	v_mul_f32_e32 v32, v32, v32
	v_mul_f32_e32 v33, v33, v33
	v_mul_f32_e32 v34, v34, v34
	v_mul_f32_e32 v35, v35, v35
	v_mul_f32_e32 v36, v36, v36
	v_mul_f32_e32 v37, v37, v37
	v_mul_f32_e32 v38, v38, v38
	v_mul_f32_e32 v39, v39, v39
	v_mul_f32_e32 v40, v40, v40
	v_mul_f32_e32 v41, v41, v41
	v_mul_f32_e32 v42, v42, v42
	v_mul_f32_e32 v43, v43, v43
	v_mul_f32_e32 v44, v44, v44
	v_mul_f32_e32 v45, v45, v45
	v_mul_f32_e32 v46, v46, v46
	v_mul_f32_e32 v47, v47, v47
	v_cvt_pk_bf16_f32 v44, v44, v45
	v_cvt_pk_bf16_f32 v45, v46, v47
	v_cvt_pk_bf16_f32 v46, v40, v41
	v_cvt_pk_bf16_f32 v47, v42, v43
	v_cvt_pk_bf16_f32 v36, v36, v37
	v_cvt_pk_bf16_f32 v37, v38, v39
	v_cvt_pk_bf16_f32 v38, v32, v33
	v_cvt_pk_bf16_f32 v39, v34, v35
	s_nop 1
	v_permlane16_swap_b32_e32 v44, v46
	v_permlane16_swap_b32_e32 v45, v47
	v_permlane16_swap_b32_e32 v36, v38
	v_permlane16_swap_b32_e32 v37, v39
	v_lshl_add_u64 v[130:131], v[132:133], 0, vcc
	s_nop 0
	global_store_dwordx4 v[132:133], v[44:47], off
	global_store_dwordx4 v[132:133], v[36:39], off offset:64
	v_max_f32_e32 v16, v16, v16
	v_max_f32_e32 v17, v17, v17
	v_max_f32_e32 v18, v18, v18
	v_max_f32_e32 v19, v19, v19
	v_max_f32_e32 v20, v20, v20
	v_max_f32_e32 v21, v21, v21
	v_max_f32_e32 v22, v22, v22
	v_max_f32_e32 v23, v23, v23
	v_max_f32_e32 v24, v24, v24
	v_max_f32_e32 v25, v25, v25
	v_max_f32_e32 v26, v26, v26
	v_max_f32_e32 v27, v27, v27
	v_max_f32_e32 v28, v28, v28
	v_max_f32_e32 v29, v29, v29
	v_max_f32_e32 v30, v30, v30
	v_max_f32_e32 v31, v31, v31
	v_max_f32_e32 v16, 0, v16
	v_max_f32_e32 v17, 0, v17
	v_max_f32_e32 v18, 0, v18
	v_max_f32_e32 v19, 0, v19
	v_max_f32_e32 v20, 0, v20
	v_max_f32_e32 v21, 0, v21
	v_max_f32_e32 v22, 0, v22
	v_max_f32_e32 v23, 0, v23
	v_max_f32_e32 v24, 0, v24
	v_max_f32_e32 v25, 0, v25
	v_max_f32_e32 v26, 0, v26
	v_max_f32_e32 v27, 0, v27
	v_max_f32_e32 v28, 0, v28
	v_max_f32_e32 v29, 0, v29
	v_max_f32_e32 v30, 0, v30
	v_max_f32_e32 v31, 0, v31
	v_mul_f32_e32 v16, v16, v16
	v_mul_f32_e32 v17, v17, v17
	v_mul_f32_e32 v18, v18, v18
	v_mul_f32_e32 v19, v19, v19
	v_mul_f32_e32 v20, v20, v20
	v_mul_f32_e32 v21, v21, v21
	v_mul_f32_e32 v22, v22, v22
	v_mul_f32_e32 v23, v23, v23
	v_mul_f32_e32 v24, v24, v24
	v_mul_f32_e32 v25, v25, v25
	v_mul_f32_e32 v26, v26, v26
	v_mul_f32_e32 v27, v27, v27
	v_mul_f32_e32 v28, v28, v28
	v_mul_f32_e32 v29, v29, v29
	v_mul_f32_e32 v30, v30, v30
	v_mul_f32_e32 v31, v31, v31
	v_cvt_pk_bf16_f32 v28, v28, v29
	v_cvt_pk_bf16_f32 v29, v30, v31
	v_cvt_pk_bf16_f32 v30, v24, v25
	v_cvt_pk_bf16_f32 v31, v26, v27
	v_cvt_pk_bf16_f32 v20, v20, v21
	v_cvt_pk_bf16_f32 v21, v22, v23
	v_cvt_pk_bf16_f32 v22, v16, v17
	v_cvt_pk_bf16_f32 v23, v18, v19
	s_nop 1
	v_permlane16_swap_b32_e32 v28, v30
	v_permlane16_swap_b32_e32 v29, v31
	v_permlane16_swap_b32_e32 v20, v22
	v_permlane16_swap_b32_e32 v21, v23
	v_lshl_add_u64 v[132:133], v[130:131], 0, vcc
	s_nop 0
	global_store_dwordx4 v[130:131], v[28:31], off
	global_store_dwordx4 v[130:131], v[20:23], off offset:64
	v_max_f32_e32 v0, v0, v0
	v_max_f32_e32 v1, v1, v1
	v_max_f32_e32 v2, v2, v2
	v_max_f32_e32 v3, v3, v3
	v_max_f32_e32 v4, v4, v4
	v_max_f32_e32 v5, v5, v5
	v_max_f32_e32 v6, v6, v6
	v_max_f32_e32 v7, v7, v7
	v_max_f32_e32 v8, v8, v8
	v_max_f32_e32 v9, v9, v9
	v_max_f32_e32 v10, v10, v10
	v_max_f32_e32 v11, v11, v11
	v_max_f32_e32 v12, v12, v12
	v_max_f32_e32 v13, v13, v13
	v_max_f32_e32 v14, v14, v14
	v_max_f32_e32 v15, v15, v15
	v_max_f32_e32 v0, 0, v0
	v_max_f32_e32 v1, 0, v1
	v_max_f32_e32 v2, 0, v2
	v_max_f32_e32 v3, 0, v3
	v_max_f32_e32 v4, 0, v4
	v_max_f32_e32 v5, 0, v5
	v_max_f32_e32 v6, 0, v6
	v_max_f32_e32 v7, 0, v7
	v_max_f32_e32 v8, 0, v8
	v_max_f32_e32 v9, 0, v9
	v_max_f32_e32 v10, 0, v10
	v_max_f32_e32 v11, 0, v11
	v_max_f32_e32 v12, 0, v12
	v_max_f32_e32 v13, 0, v13
	v_max_f32_e32 v14, 0, v14
	v_max_f32_e32 v15, 0, v15
	v_mul_f32_e32 v0, v0, v0
	v_mul_f32_e32 v1, v1, v1
	v_mul_f32_e32 v2, v2, v2
	v_mul_f32_e32 v3, v3, v3
	v_mul_f32_e32 v4, v4, v4
	v_mul_f32_e32 v5, v5, v5
	v_mul_f32_e32 v6, v6, v6
	v_mul_f32_e32 v7, v7, v7
	v_mul_f32_e32 v8, v8, v8
	v_mul_f32_e32 v9, v9, v9
	v_mul_f32_e32 v10, v10, v10
	v_mul_f32_e32 v11, v11, v11
	v_mul_f32_e32 v12, v12, v12
	v_mul_f32_e32 v13, v13, v13
	v_mul_f32_e32 v14, v14, v14
	v_mul_f32_e32 v15, v15, v15
	v_cvt_pk_bf16_f32 v12, v12, v13
	v_cvt_pk_bf16_f32 v13, v14, v15
	v_cvt_pk_bf16_f32 v14, v8, v9
	v_cvt_pk_bf16_f32 v15, v10, v11
	v_cvt_pk_bf16_f32 v4, v4, v5
	v_cvt_pk_bf16_f32 v5, v6, v7
	v_cvt_pk_bf16_f32 v6, v0, v1
	v_cvt_pk_bf16_f32 v7, v2, v3
	s_nop 1
	v_permlane16_swap_b32_e32 v12, v14
	v_permlane16_swap_b32_e32 v13, v15
	v_permlane16_swap_b32_e32 v4, v6
	v_permlane16_swap_b32_e32 v5, v7
	s_nop 0
	global_store_dwordx4 v[132:133], v[12:15], off
	global_store_dwordx4 v[132:133], v[4:7], off offset:64
	s_andn2_b64 vcc, exec, s[2:3]
	s_mov_b64 s[22:23], -1
	s_cbranch_vccz .LBB0_2207
